# band attention item start: rel-table row wait deferred past the Q/K/V requests; no store drain before the item barrier
# baseline (speedup 1.0000x reference)
.LBB0_1039:
	s_mul_hi_i32 s3, s26, 0x2aaaaaab
	s_lshr_b32 s4, s3, 31
	s_ashr_i32 s5, s3, 1
	s_add_i32 s5, s5, s4
	s_mul_i32 s0, s5, 12
	s_sub_i32 s2, s26, s0
	s_barrier
	s_and_saveexec_b64 s[0:1], s[36:37]
	s_cbranch_execz .LBB0_1041
	s_mul_i32 s6, s2, 0xc0
	s_ashr_i32 s7, s6, 31
	v_lshl_add_u64 v[0:1], s[6:7], 2, v[126:127]
	global_load_dword v237, v[0:1], off

.Lbs_nopre:
.LBB0_1043:
	s_waitcnt vmcnt(8)
	s_and_saveexec_b64 s[4:5], s[36:37]
	v_mul_f32_e32 v237, 0x3fb8aa3b, v237
	ds_write_b32 v121, v237 offset:36864
	s_or_b64 exec, exec, s[4:5]
	s_add_i32 s3, s11, s13
	s_add_i32 s4, s3, -8
	s_cmp_gt_i32 s3, 7
	s_cselect_b32 s27, s4, 0
	v_add_u32_e32 v32, s1, v144
	s_sub_i32 s28, s21, s11
	s_mul_hi_i32 s1, s0, 0x1400000
	s_mul_i32 s0, s0, 0x1400000
	s_add_u32 s0, s24, s0
	s_addc_u32 s1, s25, s1
	v_subrev_u32_e32 v133, s8, v32
	s_cmp_ge_u32 s11, 8
	s_cselect_b32 s4, s13, 0
	s_sub_i32 s27, s27, s4
	s_sub_i32 s3, s3, s4
	s_add_i32 s28, s28, s4
	s_lshl_b32 s5, s4, 6
	v_subrev_u32_e32 v133, s5, v133
	s_add_i32 s5, s30, 9
	s_cmp_ge_u32 s11, 8
	s_cselect_b32 s2, s5, s2
	v_add_u32_e32 v34, s8, v114
	v_mov_b64_e32 v[32:33], s[0:1]
	s_movk_i32 s0, 0x1400
	v_mad_i64_i32 v[32:33], s[0:1], v34, s0, v[32:33]
	v_mov_b32_e32 v34, v153
	v_mov_b32_e32 v35, v153
	v_lshl_add_u64 v[140:141], v[128:129], 0, v[32:33]
	s_cmp_ge_u32 s11, 8
	s_cselect_b32 s4, 0xf0000, 0
	s_mov_b32 s5, 0
	v_lshl_add_u64 v[140:141], v[140:141], 0, s[4:5]
	v_mov_b32_e32 v32, v153
	v_mov_b32_e32 v33, v153
	v_mov_b64_e32 v[38:39], v[34:35]
	v_mov_b64_e32 v[50:51], v[34:35]
	v_mov_b64_e32 v[42:43], v[34:35]
	v_mov_b64_e32 v[46:47], v[34:35]
	v_mov_b64_e32 v[54:55], v[34:35]
	v_mov_b64_e32 v[62:63], v[34:35]
	v_mov_b64_e32 v[58:59], v[34:35]
	v_mov_b32_e32 v131, 0
	v_mov_b32_e32 v137, 0xf149f2ca
	v_mov_b64_e32 v[36:37], v[32:33]
	v_mov_b64_e32 v[48:49], v[32:33]
	v_mov_b64_e32 v[40:41], v[32:33]
	v_mov_b64_e32 v[44:45], v[32:33]
	v_mov_b64_e32 v[52:53], v[32:33]
	v_mov_b64_e32 v[60:61], v[32:33]
	v_mov_b64_e32 v[56:57], v[32:33]
	v_mov_b32_e32 v139, 0xf149f2ca
	v_mov_b32_e32 v135, 0
